# attention jobs: one static s_setprio 1 for waves 4-7 (younger half candidate), reset at job end
# baseline (speedup 1.0000x reference)
.LBB0_595:
	s_or_b64 exec, exec, s[2:3]
	v_readlane_b32 s68, v254, 12
	s_lshl_b64 s[2:3], s[8:9], 13
	v_readlane_b32 s76, v254, 20
	v_readlane_b32 s77, v254, 21
	s_add_u32 s2, s76, s2
	s_addc_u32 s3, s77, s3
	s_add_u32 s2, s2, s20
	s_addc_u32 s3, s3, s21
	s_lshl_b32 s4, s12, 8
	s_add_u32 s2, s2, s4
	v_readlane_b32 s74, v254, 18
	s_addc_u32 s3, s3, 0
	s_mul_i32 s6, s8, 0x5040
	v_readlane_b32 s75, v254, 19
	s_mul_hi_u32 s5, s8, 0x5040
	s_add_u32 s6, s74, s6
	s_addc_u32 s5, s75, s5
	s_add_u32 s6, s6, s14
	s_addc_u32 s5, s5, s15
	s_waitcnt lgkmcnt(0)
	v_add_u32_e32 v76, v179, v176
	v_mov_b32_e32 v80, v180
	s_add_u32 s4, s6, s4
	ds_read_b128 v[64:67], v76
	ds_read_b128 v[68:71], v76 offset:32
	ds_read_b128 v[72:75], v76 offset:64
	ds_read_b128 v[76:79], v76 offset:96
	s_addc_u32 s5, s5, 0
	v_and_b32_e32 v81, 31, v80
	v_bfe_u32 v82, v80, 5, 1
	v_lshrrev_b32_e32 v83, 6, v80
	v_and_b32_e32 v84, 63, v80
	v_lshrrev_b32_e32 v92, 1, v84
	v_and_b32_e32 v93, 1, v84
	v_lshl_add_u32 v94, v83, 5, v92
	v_mov_b64_e32 v[88:89], s[4:5]
	v_mad_i64_i32 v[88:89], s[6:7], v94, s84, v[88:89]
	v_lshlrev_b32_e32 v86, 6, v93
	v_mov_b32_e32 v87, 0
	v_lshl_add_u64 v[88:89], v[88:89], 0, v[86:87]
	global_load_dwordx4 v[128:131], v[88:89], off offset:0
	global_load_dwordx4 v[132:135], v[88:89], off offset:16
	global_load_dwordx4 v[136:139], v[88:89], off offset:32
	global_load_dwordx4 v[140:143], v[88:89], off offset:48
	global_load_dwordx4 v[144:147], v[88:89], off offset:128
	global_load_dwordx4 v[148:151], v[88:89], off offset:144
	global_load_dwordx4 v[152:155], v[88:89], off offset:160
	global_load_dwordx4 v[156:159], v[88:89], off offset:176
	v_mov_b32_e32 v95, 0
	v_lshlrev_b64 v[90:91], 13, v[94:95]
	v_lshl_add_u64 v[90:91], v[90:91], 0, s[2:3]
	v_lshl_add_u64 v[90:91], v[90:91], 0, v[86:87]
	v_mul_u32_u24_e32 v85, 0x2200, v83
	v_mul_u32_u24_e32 v86, 0x110, v92
	v_lshl_add_u32 v86, v93, 7, v86
	v_add_u32_e32 v86, v85, v86
	v_mul_u32_u24_e32 v87, 0x440, v82
	v_lshl_add_u32 v87, v81, 2, v87
	v_add_u32_e32 v85, v85, v87
	s_waitcnt lgkmcnt(0)
	v_rcp_f32_e32 v64, v64
	v_rcp_f32_e32 v65, v65
	v_rcp_f32_e32 v66, v66
	v_rcp_f32_e32 v67, v67
	v_rcp_f32_e32 v68, v68
	v_rcp_f32_e32 v69, v69
	v_rcp_f32_e32 v70, v70
	v_rcp_f32_e32 v71, v71
	v_rcp_f32_e32 v72, v72
	v_rcp_f32_e32 v73, v73
	v_rcp_f32_e32 v74, v74
	v_rcp_f32_e32 v75, v75
	v_rcp_f32_e32 v76, v76
	v_rcp_f32_e32 v77, v77
	v_rcp_f32_e32 v78, v78
	v_rcp_f32_e32 v79, v79
	v_mul_f32_e32 v0, v0, v64
	v_mul_f32_e32 v1, v1, v65
	v_mul_f32_e32 v2, v2, v66
	v_mul_f32_e32 v3, v3, v67
	v_mul_f32_e32 v4, v4, v68
	v_mul_f32_e32 v5, v5, v69
	v_mul_f32_e32 v6, v6, v70
	v_mul_f32_e32 v7, v7, v71
	v_mul_f32_e32 v8, v8, v72
	v_mul_f32_e32 v9, v9, v73
	v_mul_f32_e32 v10, v10, v74
	v_mul_f32_e32 v11, v11, v75
	v_mul_f32_e32 v12, v12, v76
	v_mul_f32_e32 v13, v13, v77
	v_mul_f32_e32 v14, v14, v78
	v_mul_f32_e32 v15, v15, v79
	v_mul_f32_e32 v16, v16, v64
	v_mul_f32_e32 v17, v17, v65
	v_mul_f32_e32 v18, v18, v66
	v_mul_f32_e32 v19, v19, v67
	v_mul_f32_e32 v20, v20, v68
	v_mul_f32_e32 v21, v21, v69
	v_mul_f32_e32 v22, v22, v70
	v_mul_f32_e32 v23, v23, v71
	v_mul_f32_e32 v24, v24, v72
	v_mul_f32_e32 v25, v25, v73
	v_mul_f32_e32 v26, v26, v74
	v_mul_f32_e32 v27, v27, v75
	v_mul_f32_e32 v28, v28, v76
	v_mul_f32_e32 v29, v29, v77
	v_mul_f32_e32 v30, v30, v78
	v_mul_f32_e32 v31, v31, v79
	v_mul_f32_e32 v32, v32, v64
	v_mul_f32_e32 v33, v33, v65
	v_mul_f32_e32 v34, v34, v66
	v_mul_f32_e32 v35, v35, v67
	v_mul_f32_e32 v36, v36, v68
	v_mul_f32_e32 v37, v37, v69
	v_mul_f32_e32 v38, v38, v70
	v_mul_f32_e32 v39, v39, v71
	v_mul_f32_e32 v40, v40, v72
	v_mul_f32_e32 v41, v41, v73
	v_mul_f32_e32 v42, v42, v74
	v_mul_f32_e32 v43, v43, v75
	v_mul_f32_e32 v44, v44, v76
	v_mul_f32_e32 v45, v45, v77
	v_mul_f32_e32 v46, v46, v78
	v_mul_f32_e32 v47, v47, v79
	v_mul_f32_e32 v48, v48, v64
	v_mul_f32_e32 v49, v49, v65
	v_mul_f32_e32 v50, v50, v66
	v_mul_f32_e32 v51, v51, v67
	v_mul_f32_e32 v52, v52, v68
	v_mul_f32_e32 v53, v53, v69
	v_mul_f32_e32 v54, v54, v70
	v_mul_f32_e32 v55, v55, v71
	v_mul_f32_e32 v56, v56, v72
	v_mul_f32_e32 v57, v57, v73
	v_mul_f32_e32 v58, v58, v74
	v_mul_f32_e32 v59, v59, v75
	v_mul_f32_e32 v60, v60, v76
	v_mul_f32_e32 v61, v61, v77
	v_mul_f32_e32 v62, v62, v78
	v_mul_f32_e32 v63, v63, v79
	s_barrier
	ds_write_b32 v85, v48
	ds_write_b32 v85, v49 offset:272
	ds_write_b32 v85, v50 offset:544
	ds_write_b32 v85, v51 offset:816
	ds_write_b32 v85, v52 offset:2176
	ds_write_b32 v85, v53 offset:2448
	ds_write_b32 v85, v54 offset:2720
	ds_write_b32 v85, v55 offset:2992
	ds_write_b32 v85, v56 offset:4352
	ds_write_b32 v85, v57 offset:4624
	ds_write_b32 v85, v58 offset:4896
	ds_write_b32 v85, v59 offset:5168
	ds_write_b32 v85, v60 offset:6528
	ds_write_b32 v85, v61 offset:6800
	ds_write_b32 v85, v62 offset:7072
	ds_write_b32 v85, v63 offset:7344
	ds_write_b32 v85, v32 offset:128
	ds_write_b32 v85, v33 offset:400
	ds_write_b32 v85, v34 offset:672
	ds_write_b32 v85, v35 offset:944
	ds_write_b32 v85, v36 offset:2304
	ds_write_b32 v85, v37 offset:2576
	ds_write_b32 v85, v38 offset:2848
	ds_write_b32 v85, v39 offset:3120
	ds_write_b32 v85, v40 offset:4480
	ds_write_b32 v85, v41 offset:4752
	ds_write_b32 v85, v42 offset:5024
	ds_write_b32 v85, v43 offset:5296
	ds_write_b32 v85, v44 offset:6656
	ds_write_b32 v85, v45 offset:6928
	ds_write_b32 v85, v46 offset:7200
	ds_write_b32 v85, v47 offset:7472
	s_waitcnt lgkmcnt(0)
	ds_read_b128 v[96:99], v86
	ds_read_b128 v[100:103], v86 offset:16
	ds_read_b128 v[104:107], v86 offset:32
	ds_read_b128 v[108:111], v86 offset:48
	ds_read_b128 v[112:115], v86 offset:64
	ds_read_b128 v[116:119], v86 offset:80
	ds_read_b128 v[120:123], v86 offset:96
	ds_read_b128 v[124:127], v86 offset:112
	s_waitcnt vmcnt(4) lgkmcnt(0)
	v_lshlrev_b32_e32 v186, 16, v128
	v_and_b32_e32 v187, 0xffff0000, v128
	v_lshlrev_b32_e32 v188, 16, v129
	v_and_b32_e32 v189, 0xffff0000, v129
	v_mul_f32_e32 v224, 0xbfb8aa3b, v186
	v_mul_f32_e32 v225, 0xbfb8aa3b, v187
	v_mul_f32_e32 v226, 0xbfb8aa3b, v188
	v_mul_f32_e32 v227, 0xbfb8aa3b, v189
	v_exp_f32_e32 v224, v224
	v_exp_f32_e32 v225, v225
	v_exp_f32_e32 v226, v226
	v_exp_f32_e32 v227, v227
	v_add_f32_e32 v224, 1.0, v224
	v_add_f32_e32 v225, 1.0, v225
	v_add_f32_e32 v226, 1.0, v226
	v_add_f32_e32 v227, 1.0, v227
	v_rcp_f32_e32 v224, v224
	v_rcp_f32_e32 v225, v225
	v_rcp_f32_e32 v226, v226
	v_rcp_f32_e32 v227, v227
	v_mul_f32_e32 v186, v224, v186
	v_mul_f32_e32 v187, v225, v187
	v_mul_f32_e32 v188, v226, v188
	v_mul_f32_e32 v189, v227, v189
	v_mul_f32_e32 v186, v96, v186
	v_mul_f32_e32 v187, v97, v187
	v_mul_f32_e32 v188, v98, v188
	v_mul_f32_e32 v189, v99, v189
	v_lshlrev_b32_e32 v190, 16, v130
	v_and_b32_e32 v191, 0xffff0000, v130
	v_lshlrev_b32_e32 v192, 16, v131
	v_and_b32_e32 v193, 0xffff0000, v131
	v_mul_f32_e32 v224, 0xbfb8aa3b, v190
	v_mul_f32_e32 v225, 0xbfb8aa3b, v191
	v_mul_f32_e32 v226, 0xbfb8aa3b, v192
	v_mul_f32_e32 v227, 0xbfb8aa3b, v193
	v_exp_f32_e32 v224, v224
	v_exp_f32_e32 v225, v225
	v_exp_f32_e32 v226, v226
	v_exp_f32_e32 v227, v227
	v_add_f32_e32 v224, 1.0, v224
	v_add_f32_e32 v225, 1.0, v225
	v_add_f32_e32 v226, 1.0, v226
	v_add_f32_e32 v227, 1.0, v227
	v_rcp_f32_e32 v224, v224
	v_rcp_f32_e32 v225, v225
	v_rcp_f32_e32 v226, v226
	v_rcp_f32_e32 v227, v227
	v_mul_f32_e32 v190, v224, v190
	v_mul_f32_e32 v191, v225, v191
	v_mul_f32_e32 v192, v226, v192
	v_mul_f32_e32 v193, v227, v193
	v_mul_f32_e32 v190, v100, v190
	v_mul_f32_e32 v191, v101, v191
	v_mul_f32_e32 v192, v102, v192
	v_mul_f32_e32 v193, v103, v193
	v_lshlrev_b32_e32 v194, 16, v132
	v_and_b32_e32 v195, 0xffff0000, v132
	v_lshlrev_b32_e32 v196, 16, v133
	v_and_b32_e32 v197, 0xffff0000, v133
	v_mul_f32_e32 v224, 0xbfb8aa3b, v194
	v_mul_f32_e32 v225, 0xbfb8aa3b, v195
	v_mul_f32_e32 v226, 0xbfb8aa3b, v196
	v_mul_f32_e32 v227, 0xbfb8aa3b, v197
	v_exp_f32_e32 v224, v224
	v_exp_f32_e32 v225, v225
	v_exp_f32_e32 v226, v226
	v_exp_f32_e32 v227, v227
	v_add_f32_e32 v224, 1.0, v224
	v_add_f32_e32 v225, 1.0, v225
	v_add_f32_e32 v226, 1.0, v226
	v_add_f32_e32 v227, 1.0, v227
	v_rcp_f32_e32 v224, v224
	v_rcp_f32_e32 v225, v225
	v_rcp_f32_e32 v226, v226
	v_rcp_f32_e32 v227, v227
	v_mul_f32_e32 v194, v224, v194
	v_mul_f32_e32 v195, v225, v195
	v_mul_f32_e32 v196, v226, v196
	v_mul_f32_e32 v197, v227, v197
	v_mul_f32_e32 v194, v104, v194
	v_mul_f32_e32 v195, v105, v195
	v_mul_f32_e32 v196, v106, v196
	v_mul_f32_e32 v197, v107, v197
	v_lshlrev_b32_e32 v198, 16, v134
	v_and_b32_e32 v199, 0xffff0000, v134
	v_lshlrev_b32_e32 v200, 16, v135
	v_and_b32_e32 v201, 0xffff0000, v135
	v_mul_f32_e32 v224, 0xbfb8aa3b, v198
	v_mul_f32_e32 v225, 0xbfb8aa3b, v199
	v_mul_f32_e32 v226, 0xbfb8aa3b, v200
	v_mul_f32_e32 v227, 0xbfb8aa3b, v201
	v_exp_f32_e32 v224, v224
	v_exp_f32_e32 v225, v225
	v_exp_f32_e32 v226, v226
	v_exp_f32_e32 v227, v227
	v_add_f32_e32 v224, 1.0, v224
	v_add_f32_e32 v225, 1.0, v225
	v_add_f32_e32 v226, 1.0, v226
	v_add_f32_e32 v227, 1.0, v227
	v_rcp_f32_e32 v224, v224
	v_rcp_f32_e32 v225, v225
	v_rcp_f32_e32 v226, v226
	v_rcp_f32_e32 v227, v227
	v_mul_f32_e32 v198, v224, v198
	v_mul_f32_e32 v199, v225, v199
	v_mul_f32_e32 v200, v226, v200
	v_mul_f32_e32 v201, v227, v201
	v_mul_f32_e32 v198, v108, v198
	v_mul_f32_e32 v199, v109, v199
	v_mul_f32_e32 v200, v110, v200
	v_mul_f32_e32 v201, v111, v201
	v_lshlrev_b32_e32 v202, 16, v136
	v_and_b32_e32 v203, 0xffff0000, v136
	v_lshlrev_b32_e32 v204, 16, v137
	v_and_b32_e32 v205, 0xffff0000, v137
	v_mul_f32_e32 v224, 0xbfb8aa3b, v202
	v_mul_f32_e32 v225, 0xbfb8aa3b, v203
	v_mul_f32_e32 v226, 0xbfb8aa3b, v204
	v_mul_f32_e32 v227, 0xbfb8aa3b, v205
	v_exp_f32_e32 v224, v224
	v_exp_f32_e32 v225, v225
	v_exp_f32_e32 v226, v226
	v_exp_f32_e32 v227, v227
	v_add_f32_e32 v224, 1.0, v224
	v_add_f32_e32 v225, 1.0, v225
	v_add_f32_e32 v226, 1.0, v226
	v_add_f32_e32 v227, 1.0, v227
	v_rcp_f32_e32 v224, v224
	v_rcp_f32_e32 v225, v225
	v_rcp_f32_e32 v226, v226
	v_rcp_f32_e32 v227, v227
	v_mul_f32_e32 v202, v224, v202
	v_mul_f32_e32 v203, v225, v203
	v_mul_f32_e32 v204, v226, v204
	v_mul_f32_e32 v205, v227, v205
	v_mul_f32_e32 v202, v112, v202
	v_mul_f32_e32 v203, v113, v203
	v_mul_f32_e32 v204, v114, v204
	v_mul_f32_e32 v205, v115, v205
	v_lshlrev_b32_e32 v206, 16, v138
	v_and_b32_e32 v207, 0xffff0000, v138
	v_lshlrev_b32_e32 v208, 16, v139
	v_and_b32_e32 v209, 0xffff0000, v139
	v_mul_f32_e32 v224, 0xbfb8aa3b, v206
	v_mul_f32_e32 v225, 0xbfb8aa3b, v207
	v_mul_f32_e32 v226, 0xbfb8aa3b, v208
	v_mul_f32_e32 v227, 0xbfb8aa3b, v209
	v_exp_f32_e32 v224, v224
	v_exp_f32_e32 v225, v225
	v_exp_f32_e32 v226, v226
	v_exp_f32_e32 v227, v227
	v_add_f32_e32 v224, 1.0, v224
	v_add_f32_e32 v225, 1.0, v225
	v_add_f32_e32 v226, 1.0, v226
	v_add_f32_e32 v227, 1.0, v227
	v_rcp_f32_e32 v224, v224
	v_rcp_f32_e32 v225, v225
	v_rcp_f32_e32 v226, v226
	v_rcp_f32_e32 v227, v227
	v_mul_f32_e32 v206, v224, v206
	v_mul_f32_e32 v207, v225, v207
	v_mul_f32_e32 v208, v226, v208
	v_mul_f32_e32 v209, v227, v209
	v_mul_f32_e32 v206, v116, v206
	v_mul_f32_e32 v207, v117, v207
	v_mul_f32_e32 v208, v118, v208
	v_mul_f32_e32 v209, v119, v209
	v_lshlrev_b32_e32 v210, 16, v140
	v_and_b32_e32 v211, 0xffff0000, v140
	v_lshlrev_b32_e32 v212, 16, v141
	v_and_b32_e32 v213, 0xffff0000, v141
	v_mul_f32_e32 v224, 0xbfb8aa3b, v210
	v_mul_f32_e32 v225, 0xbfb8aa3b, v211
	v_mul_f32_e32 v226, 0xbfb8aa3b, v212
	v_mul_f32_e32 v227, 0xbfb8aa3b, v213
	v_exp_f32_e32 v224, v224
	v_exp_f32_e32 v225, v225
	v_exp_f32_e32 v226, v226
	v_exp_f32_e32 v227, v227
	v_add_f32_e32 v224, 1.0, v224
	v_add_f32_e32 v225, 1.0, v225
	v_add_f32_e32 v226, 1.0, v226
	v_add_f32_e32 v227, 1.0, v227
	v_rcp_f32_e32 v224, v224
	v_rcp_f32_e32 v225, v225
	v_rcp_f32_e32 v226, v226
	v_rcp_f32_e32 v227, v227
	v_mul_f32_e32 v210, v224, v210
	v_mul_f32_e32 v211, v225, v211
	v_mul_f32_e32 v212, v226, v212
	v_mul_f32_e32 v213, v227, v213
	v_mul_f32_e32 v210, v120, v210
	v_mul_f32_e32 v211, v121, v211
	v_mul_f32_e32 v212, v122, v212
	v_mul_f32_e32 v213, v123, v213
	v_lshlrev_b32_e32 v214, 16, v142
	v_and_b32_e32 v215, 0xffff0000, v142
	v_lshlrev_b32_e32 v216, 16, v143
	v_and_b32_e32 v217, 0xffff0000, v143
	v_mul_f32_e32 v224, 0xbfb8aa3b, v214
	v_mul_f32_e32 v225, 0xbfb8aa3b, v215
	v_mul_f32_e32 v226, 0xbfb8aa3b, v216
	v_mul_f32_e32 v227, 0xbfb8aa3b, v217
	v_exp_f32_e32 v224, v224
	v_exp_f32_e32 v225, v225
	v_exp_f32_e32 v226, v226
	v_exp_f32_e32 v227, v227
	v_add_f32_e32 v224, 1.0, v224
	v_add_f32_e32 v225, 1.0, v225
	v_add_f32_e32 v226, 1.0, v226
	v_add_f32_e32 v227, 1.0, v227
	v_rcp_f32_e32 v224, v224
	v_rcp_f32_e32 v225, v225
	v_rcp_f32_e32 v226, v226
	v_rcp_f32_e32 v227, v227
	v_mul_f32_e32 v214, v224, v214
	v_mul_f32_e32 v215, v225, v215
	v_mul_f32_e32 v216, v226, v216
	v_mul_f32_e32 v217, v227, v217
	v_mul_f32_e32 v214, v124, v214
	v_mul_f32_e32 v215, v125, v215
	v_mul_f32_e32 v216, v126, v216
	v_mul_f32_e32 v217, v127, v217
	v_cvt_pk_bf16_f32 v96, v186, v187
	v_cvt_pk_bf16_f32 v97, v188, v189
	v_cvt_pk_bf16_f32 v98, v190, v191
	v_cvt_pk_bf16_f32 v99, v192, v193
	v_cvt_pk_bf16_f32 v100, v194, v195
	v_cvt_pk_bf16_f32 v101, v196, v197
	v_cvt_pk_bf16_f32 v102, v198, v199
	v_cvt_pk_bf16_f32 v103, v200, v201
	v_cvt_pk_bf16_f32 v104, v202, v203
	v_cvt_pk_bf16_f32 v105, v204, v205
	v_cvt_pk_bf16_f32 v106, v206, v207
	v_cvt_pk_bf16_f32 v107, v208, v209
	v_cvt_pk_bf16_f32 v108, v210, v211
	v_cvt_pk_bf16_f32 v109, v212, v213
	v_cvt_pk_bf16_f32 v110, v214, v215
	v_cvt_pk_bf16_f32 v111, v216, v217
	global_store_dwordx4 v[90:91], v[96:99], off offset:0
	global_store_dwordx4 v[90:91], v[100:103], off offset:16
	global_store_dwordx4 v[90:91], v[104:107], off offset:32
	global_store_dwordx4 v[90:91], v[108:111], off offset:48
	ds_write_b32 v85, v16
	ds_write_b32 v85, v17 offset:272
	ds_write_b32 v85, v18 offset:544
	ds_write_b32 v85, v19 offset:816
	ds_write_b32 v85, v20 offset:2176
	ds_write_b32 v85, v21 offset:2448
	ds_write_b32 v85, v22 offset:2720
	ds_write_b32 v85, v23 offset:2992
	ds_write_b32 v85, v24 offset:4352
	ds_write_b32 v85, v25 offset:4624
	ds_write_b32 v85, v26 offset:4896
	ds_write_b32 v85, v27 offset:5168
	ds_write_b32 v85, v28 offset:6528
	ds_write_b32 v85, v29 offset:6800
	ds_write_b32 v85, v30 offset:7072
	ds_write_b32 v85, v31 offset:7344
	ds_write_b32 v85, v0 offset:128
	ds_write_b32 v85, v1 offset:400
	ds_write_b32 v85, v2 offset:672
	ds_write_b32 v85, v3 offset:944
	ds_write_b32 v85, v4 offset:2304
	ds_write_b32 v85, v5 offset:2576
	ds_write_b32 v85, v6 offset:2848
	ds_write_b32 v85, v7 offset:3120
	ds_write_b32 v85, v8 offset:4480
	ds_write_b32 v85, v9 offset:4752
	ds_write_b32 v85, v10 offset:5024
	ds_write_b32 v85, v11 offset:5296
	ds_write_b32 v85, v12 offset:6656
	ds_write_b32 v85, v13 offset:6928
	ds_write_b32 v85, v14 offset:7200
	ds_write_b32 v85, v15 offset:7472
	s_waitcnt lgkmcnt(0)
	ds_read_b128 v[96:99], v86
	ds_read_b128 v[100:103], v86 offset:16
	ds_read_b128 v[104:107], v86 offset:32
	ds_read_b128 v[108:111], v86 offset:48
	ds_read_b128 v[112:115], v86 offset:64
	ds_read_b128 v[116:119], v86 offset:80
	ds_read_b128 v[120:123], v86 offset:96
	ds_read_b128 v[124:127], v86 offset:112
	s_waitcnt vmcnt(4) lgkmcnt(0)
	v_lshlrev_b32_e32 v186, 16, v144
	v_and_b32_e32 v187, 0xffff0000, v144
	v_lshlrev_b32_e32 v188, 16, v145
	v_and_b32_e32 v189, 0xffff0000, v145
	v_mul_f32_e32 v224, 0xbfb8aa3b, v186
	v_mul_f32_e32 v225, 0xbfb8aa3b, v187
	v_mul_f32_e32 v226, 0xbfb8aa3b, v188
	v_mul_f32_e32 v227, 0xbfb8aa3b, v189
	v_exp_f32_e32 v224, v224
	v_exp_f32_e32 v225, v225
	v_exp_f32_e32 v226, v226
	v_exp_f32_e32 v227, v227
	v_add_f32_e32 v224, 1.0, v224
	v_add_f32_e32 v225, 1.0, v225
	v_add_f32_e32 v226, 1.0, v226
	v_add_f32_e32 v227, 1.0, v227
	v_rcp_f32_e32 v224, v224
	v_rcp_f32_e32 v225, v225
	v_rcp_f32_e32 v226, v226
	v_rcp_f32_e32 v227, v227
	v_mul_f32_e32 v186, v224, v186
	v_mul_f32_e32 v187, v225, v187
	v_mul_f32_e32 v188, v226, v188
	v_mul_f32_e32 v189, v227, v189
	v_mul_f32_e32 v186, v96, v186
	v_mul_f32_e32 v187, v97, v187
	v_mul_f32_e32 v188, v98, v188
	v_mul_f32_e32 v189, v99, v189
	v_lshlrev_b32_e32 v190, 16, v146
	v_and_b32_e32 v191, 0xffff0000, v146
	v_lshlrev_b32_e32 v192, 16, v147
	v_and_b32_e32 v193, 0xffff0000, v147
	v_mul_f32_e32 v224, 0xbfb8aa3b, v190
	v_mul_f32_e32 v225, 0xbfb8aa3b, v191
	v_mul_f32_e32 v226, 0xbfb8aa3b, v192
	v_mul_f32_e32 v227, 0xbfb8aa3b, v193
	v_exp_f32_e32 v224, v224
	v_exp_f32_e32 v225, v225
	v_exp_f32_e32 v226, v226
	v_exp_f32_e32 v227, v227
	v_add_f32_e32 v224, 1.0, v224
	v_add_f32_e32 v225, 1.0, v225
	v_add_f32_e32 v226, 1.0, v226
	v_add_f32_e32 v227, 1.0, v227
	v_rcp_f32_e32 v224, v224
	v_rcp_f32_e32 v225, v225
	v_rcp_f32_e32 v226, v226
	v_rcp_f32_e32 v227, v227
	v_mul_f32_e32 v190, v224, v190
	v_mul_f32_e32 v191, v225, v191
	v_mul_f32_e32 v192, v226, v192
	v_mul_f32_e32 v193, v227, v193
	v_mul_f32_e32 v190, v100, v190
	v_mul_f32_e32 v191, v101, v191
	v_mul_f32_e32 v192, v102, v192
	v_mul_f32_e32 v193, v103, v193
	v_lshlrev_b32_e32 v194, 16, v148
	v_and_b32_e32 v195, 0xffff0000, v148
	v_lshlrev_b32_e32 v196, 16, v149
	v_and_b32_e32 v197, 0xffff0000, v149
	v_mul_f32_e32 v224, 0xbfb8aa3b, v194
	v_mul_f32_e32 v225, 0xbfb8aa3b, v195
	v_mul_f32_e32 v226, 0xbfb8aa3b, v196
	v_mul_f32_e32 v227, 0xbfb8aa3b, v197
	v_exp_f32_e32 v224, v224
	v_exp_f32_e32 v225, v225
	v_exp_f32_e32 v226, v226
	v_exp_f32_e32 v227, v227
	v_add_f32_e32 v224, 1.0, v224
	v_add_f32_e32 v225, 1.0, v225
	v_add_f32_e32 v226, 1.0, v226
	v_add_f32_e32 v227, 1.0, v227
	v_rcp_f32_e32 v224, v224
	v_rcp_f32_e32 v225, v225
	v_rcp_f32_e32 v226, v226
	v_rcp_f32_e32 v227, v227
	v_mul_f32_e32 v194, v224, v194
	v_mul_f32_e32 v195, v225, v195
	v_mul_f32_e32 v196, v226, v196
	v_mul_f32_e32 v197, v227, v197
	v_mul_f32_e32 v194, v104, v194
	v_mul_f32_e32 v195, v105, v195
	v_mul_f32_e32 v196, v106, v196
	v_mul_f32_e32 v197, v107, v197
	v_lshlrev_b32_e32 v198, 16, v150
	v_and_b32_e32 v199, 0xffff0000, v150
	v_lshlrev_b32_e32 v200, 16, v151
	v_and_b32_e32 v201, 0xffff0000, v151
	v_mul_f32_e32 v224, 0xbfb8aa3b, v198
	v_mul_f32_e32 v225, 0xbfb8aa3b, v199
	v_mul_f32_e32 v226, 0xbfb8aa3b, v200
	v_mul_f32_e32 v227, 0xbfb8aa3b, v201
	v_exp_f32_e32 v224, v224
	v_exp_f32_e32 v225, v225
	v_exp_f32_e32 v226, v226
	v_exp_f32_e32 v227, v227
	v_add_f32_e32 v224, 1.0, v224
	v_add_f32_e32 v225, 1.0, v225
	v_add_f32_e32 v226, 1.0, v226
	v_add_f32_e32 v227, 1.0, v227
	v_rcp_f32_e32 v224, v224
	v_rcp_f32_e32 v225, v225
	v_rcp_f32_e32 v226, v226
	v_rcp_f32_e32 v227, v227
	v_mul_f32_e32 v198, v224, v198
	v_mul_f32_e32 v199, v225, v199
	v_mul_f32_e32 v200, v226, v200
	v_mul_f32_e32 v201, v227, v201
	v_mul_f32_e32 v198, v108, v198
	v_mul_f32_e32 v199, v109, v199
	v_mul_f32_e32 v200, v110, v200
	v_mul_f32_e32 v201, v111, v201
	v_lshlrev_b32_e32 v202, 16, v152
	v_and_b32_e32 v203, 0xffff0000, v152
	v_lshlrev_b32_e32 v204, 16, v153
	v_and_b32_e32 v205, 0xffff0000, v153
	v_mul_f32_e32 v224, 0xbfb8aa3b, v202
	v_mul_f32_e32 v225, 0xbfb8aa3b, v203
	v_mul_f32_e32 v226, 0xbfb8aa3b, v204
	v_mul_f32_e32 v227, 0xbfb8aa3b, v205
	v_exp_f32_e32 v224, v224
	v_exp_f32_e32 v225, v225
	v_exp_f32_e32 v226, v226
	v_exp_f32_e32 v227, v227
	v_add_f32_e32 v224, 1.0, v224
	v_add_f32_e32 v225, 1.0, v225
	v_add_f32_e32 v226, 1.0, v226
	v_add_f32_e32 v227, 1.0, v227
	v_rcp_f32_e32 v224, v224
	v_rcp_f32_e32 v225, v225
	v_rcp_f32_e32 v226, v226
	v_rcp_f32_e32 v227, v227
	v_mul_f32_e32 v202, v224, v202
	v_mul_f32_e32 v203, v225, v203
	v_mul_f32_e32 v204, v226, v204
	v_mul_f32_e32 v205, v227, v205
	v_mul_f32_e32 v202, v112, v202
	v_mul_f32_e32 v203, v113, v203
	v_mul_f32_e32 v204, v114, v204
	v_mul_f32_e32 v205, v115, v205
	v_lshlrev_b32_e32 v206, 16, v154
	v_and_b32_e32 v207, 0xffff0000, v154
	v_lshlrev_b32_e32 v208, 16, v155
	v_and_b32_e32 v209, 0xffff0000, v155
	v_mul_f32_e32 v224, 0xbfb8aa3b, v206
	v_mul_f32_e32 v225, 0xbfb8aa3b, v207
	v_mul_f32_e32 v226, 0xbfb8aa3b, v208
	v_mul_f32_e32 v227, 0xbfb8aa3b, v209
	v_exp_f32_e32 v224, v224
	v_exp_f32_e32 v225, v225
	v_exp_f32_e32 v226, v226
	v_exp_f32_e32 v227, v227
	v_add_f32_e32 v224, 1.0, v224
	v_add_f32_e32 v225, 1.0, v225
	v_add_f32_e32 v226, 1.0, v226
	v_add_f32_e32 v227, 1.0, v227
	v_rcp_f32_e32 v224, v224
	v_rcp_f32_e32 v225, v225
	v_rcp_f32_e32 v226, v226
	v_rcp_f32_e32 v227, v227
	v_mul_f32_e32 v206, v224, v206
	v_mul_f32_e32 v207, v225, v207
	v_mul_f32_e32 v208, v226, v208
	v_mul_f32_e32 v209, v227, v209
	v_mul_f32_e32 v206, v116, v206
	v_mul_f32_e32 v207, v117, v207
	v_mul_f32_e32 v208, v118, v208
	v_mul_f32_e32 v209, v119, v209
	v_lshlrev_b32_e32 v210, 16, v156
	v_and_b32_e32 v211, 0xffff0000, v156
	v_lshlrev_b32_e32 v212, 16, v157
	v_and_b32_e32 v213, 0xffff0000, v157
	v_mul_f32_e32 v224, 0xbfb8aa3b, v210
	v_mul_f32_e32 v225, 0xbfb8aa3b, v211
	v_mul_f32_e32 v226, 0xbfb8aa3b, v212
	v_mul_f32_e32 v227, 0xbfb8aa3b, v213
	v_exp_f32_e32 v224, v224
	v_exp_f32_e32 v225, v225
	v_exp_f32_e32 v226, v226
	v_exp_f32_e32 v227, v227
	v_add_f32_e32 v224, 1.0, v224
	v_add_f32_e32 v225, 1.0, v225
	v_add_f32_e32 v226, 1.0, v226
	v_add_f32_e32 v227, 1.0, v227
	v_rcp_f32_e32 v224, v224
	v_rcp_f32_e32 v225, v225
	v_rcp_f32_e32 v226, v226
	v_rcp_f32_e32 v227, v227
	v_mul_f32_e32 v210, v224, v210
	v_mul_f32_e32 v211, v225, v211
	v_mul_f32_e32 v212, v226, v212
	v_mul_f32_e32 v213, v227, v213
	v_mul_f32_e32 v210, v120, v210
	v_mul_f32_e32 v211, v121, v211
	v_mul_f32_e32 v212, v122, v212
	v_mul_f32_e32 v213, v123, v213
	v_lshlrev_b32_e32 v214, 16, v158
	v_and_b32_e32 v215, 0xffff0000, v158
	v_lshlrev_b32_e32 v216, 16, v159
	v_and_b32_e32 v217, 0xffff0000, v159
	v_mul_f32_e32 v224, 0xbfb8aa3b, v214
	v_mul_f32_e32 v225, 0xbfb8aa3b, v215
	v_mul_f32_e32 v226, 0xbfb8aa3b, v216
	v_mul_f32_e32 v227, 0xbfb8aa3b, v217
	v_exp_f32_e32 v224, v224
	v_exp_f32_e32 v225, v225
	v_exp_f32_e32 v226, v226
	v_exp_f32_e32 v227, v227
	v_add_f32_e32 v224, 1.0, v224
	v_add_f32_e32 v225, 1.0, v225
	v_add_f32_e32 v226, 1.0, v226
	v_add_f32_e32 v227, 1.0, v227
	v_rcp_f32_e32 v224, v224
	v_rcp_f32_e32 v225, v225
	v_rcp_f32_e32 v226, v226
	v_rcp_f32_e32 v227, v227
	v_mul_f32_e32 v214, v224, v214
	v_mul_f32_e32 v215, v225, v215
	v_mul_f32_e32 v216, v226, v216
	v_mul_f32_e32 v217, v227, v217
	v_mul_f32_e32 v214, v124, v214
	v_mul_f32_e32 v215, v125, v215
	v_mul_f32_e32 v216, v126, v216
	v_mul_f32_e32 v217, v127, v217
	v_cvt_pk_bf16_f32 v96, v186, v187
	v_cvt_pk_bf16_f32 v97, v188, v189
	v_cvt_pk_bf16_f32 v98, v190, v191
	v_cvt_pk_bf16_f32 v99, v192, v193
	v_cvt_pk_bf16_f32 v100, v194, v195
	v_cvt_pk_bf16_f32 v101, v196, v197
	v_cvt_pk_bf16_f32 v102, v198, v199
	v_cvt_pk_bf16_f32 v103, v200, v201
	v_cvt_pk_bf16_f32 v104, v202, v203
	v_cvt_pk_bf16_f32 v105, v204, v205
	v_cvt_pk_bf16_f32 v106, v206, v207
	v_cvt_pk_bf16_f32 v107, v208, v209
	v_cvt_pk_bf16_f32 v108, v210, v211
	v_cvt_pk_bf16_f32 v109, v212, v213
	v_cvt_pk_bf16_f32 v110, v214, v215
	v_cvt_pk_bf16_f32 v111, v216, v217
	global_store_dwordx4 v[90:91], v[96:99], off offset:128
	global_store_dwordx4 v[90:91], v[100:103], off offset:144
	global_store_dwordx4 v[90:91], v[104:107], off offset:160
	global_store_dwordx4 v[90:91], v[108:111], off offset:176
	s_add_i32 s4, s35, 1
	s_cmp_lt_u32 s35, 2
	s_mov_b32 s35, s4
	s_cselect_b64 s[2:3], -1, 0
	s_and_b64 s[2:3], s[0:1], s[2:3]
	s_andn2_b64 vcc, exec, s[2:3]
	s_setprio 0
	s_waitcnt vmcnt(63) expcnt(7) lgkmcnt(15)
	s_barrier
	s_cbranch_vccnz .LBB0_642
.LBB0_596:
	v_readfirstlane_b32 s2, v180
	s_lshr_b32 s2, s2, 8
	s_cmp_eq_u32 s2, 1
	s_cbranch_scc0 .Lprio0_skip
	s_setprio 1

.LBB0_1306:
	s_or_b64 exec, exec, s[2:3]
	v_readlane_b32 s64, v254, 12
	s_lshl_b64 s[2:3], s[8:9], 13
	v_readlane_b32 s72, v254, 20
	v_readlane_b32 s73, v254, 21
	s_add_u32 s2, s72, s2
	s_addc_u32 s3, s73, s3
	s_add_u32 s2, s2, s18
	s_addc_u32 s3, s3, s19
	s_lshl_b32 s4, s12, 8
	s_add_u32 s2, s2, s4
	v_readlane_b32 s70, v254, 18
	s_addc_u32 s3, s3, 0
	s_mul_i32 s6, s8, 0x5040
	v_readlane_b32 s71, v254, 19
	s_mul_hi_u32 s5, s8, 0x5040
	s_add_u32 s6, s70, s6
	s_addc_u32 s5, s71, s5
	s_add_u32 s6, s6, s14
	s_addc_u32 s5, s5, s15
	s_waitcnt lgkmcnt(0)
	v_add_u32_e32 v76, v179, v176
	v_mov_b32_e32 v80, v180
	s_add_u32 s4, s6, s4
	ds_read_b128 v[64:67], v76
	ds_read_b128 v[68:71], v76 offset:32
	ds_read_b128 v[72:75], v76 offset:64
	ds_read_b128 v[76:79], v76 offset:96
	s_addc_u32 s5, s5, 0
	v_and_b32_e32 v81, 31, v80
	v_bfe_u32 v82, v80, 5, 1
	v_lshrrev_b32_e32 v83, 6, v80
	v_and_b32_e32 v84, 63, v80
	v_lshrrev_b32_e32 v92, 1, v84
	v_and_b32_e32 v93, 1, v84
	v_lshl_add_u32 v94, v83, 5, v92
	v_mov_b64_e32 v[88:89], s[4:5]
	v_mad_i64_i32 v[88:89], s[6:7], v94, s52, v[88:89]
	v_lshlrev_b32_e32 v86, 6, v93
	v_mov_b32_e32 v87, 0
	v_lshl_add_u64 v[88:89], v[88:89], 0, v[86:87]
	global_load_dwordx4 v[128:131], v[88:89], off offset:0
	global_load_dwordx4 v[132:135], v[88:89], off offset:16
	global_load_dwordx4 v[136:139], v[88:89], off offset:32
	global_load_dwordx4 v[140:143], v[88:89], off offset:48
	global_load_dwordx4 v[144:147], v[88:89], off offset:128
	global_load_dwordx4 v[148:151], v[88:89], off offset:144
	global_load_dwordx4 v[152:155], v[88:89], off offset:160
	global_load_dwordx4 v[156:159], v[88:89], off offset:176
	v_mov_b32_e32 v95, 0
	v_lshlrev_b64 v[90:91], 13, v[94:95]
	v_lshl_add_u64 v[90:91], v[90:91], 0, s[2:3]
	v_lshl_add_u64 v[90:91], v[90:91], 0, v[86:87]
	v_mul_u32_u24_e32 v85, 0x2200, v83
	v_mul_u32_u24_e32 v86, 0x110, v92
	v_lshl_add_u32 v86, v93, 7, v86
	v_add_u32_e32 v86, v85, v86
	v_mul_u32_u24_e32 v87, 0x440, v82
	v_lshl_add_u32 v87, v81, 2, v87
	v_add_u32_e32 v85, v85, v87
	s_waitcnt lgkmcnt(0)
	v_rcp_f32_e32 v64, v64
	v_rcp_f32_e32 v65, v65
	v_rcp_f32_e32 v66, v66
	v_rcp_f32_e32 v67, v67
	v_rcp_f32_e32 v68, v68
	v_rcp_f32_e32 v69, v69
	v_rcp_f32_e32 v70, v70
	v_rcp_f32_e32 v71, v71
	v_rcp_f32_e32 v72, v72
	v_rcp_f32_e32 v73, v73
	v_rcp_f32_e32 v74, v74
	v_rcp_f32_e32 v75, v75
	v_rcp_f32_e32 v76, v76
	v_rcp_f32_e32 v77, v77
	v_rcp_f32_e32 v78, v78
	v_rcp_f32_e32 v79, v79
	v_mul_f32_e32 v0, v0, v64
	v_mul_f32_e32 v1, v1, v65
	v_mul_f32_e32 v2, v2, v66
	v_mul_f32_e32 v3, v3, v67
	v_mul_f32_e32 v4, v4, v68
	v_mul_f32_e32 v5, v5, v69
	v_mul_f32_e32 v6, v6, v70
	v_mul_f32_e32 v7, v7, v71
	v_mul_f32_e32 v8, v8, v72
	v_mul_f32_e32 v9, v9, v73
	v_mul_f32_e32 v10, v10, v74
	v_mul_f32_e32 v11, v11, v75
	v_mul_f32_e32 v12, v12, v76
	v_mul_f32_e32 v13, v13, v77
	v_mul_f32_e32 v14, v14, v78
	v_mul_f32_e32 v15, v15, v79
	v_mul_f32_e32 v16, v16, v64
	v_mul_f32_e32 v17, v17, v65
	v_mul_f32_e32 v18, v18, v66
	v_mul_f32_e32 v19, v19, v67
	v_mul_f32_e32 v20, v20, v68
	v_mul_f32_e32 v21, v21, v69
	v_mul_f32_e32 v22, v22, v70
	v_mul_f32_e32 v23, v23, v71
	v_mul_f32_e32 v24, v24, v72
	v_mul_f32_e32 v25, v25, v73
	v_mul_f32_e32 v26, v26, v74
	v_mul_f32_e32 v27, v27, v75
	v_mul_f32_e32 v28, v28, v76
	v_mul_f32_e32 v29, v29, v77
	v_mul_f32_e32 v30, v30, v78
	v_mul_f32_e32 v31, v31, v79
	v_mul_f32_e32 v32, v32, v64
	v_mul_f32_e32 v33, v33, v65
	v_mul_f32_e32 v34, v34, v66
	v_mul_f32_e32 v35, v35, v67
	v_mul_f32_e32 v36, v36, v68
	v_mul_f32_e32 v37, v37, v69
	v_mul_f32_e32 v38, v38, v70
	v_mul_f32_e32 v39, v39, v71
	v_mul_f32_e32 v40, v40, v72
	v_mul_f32_e32 v41, v41, v73
	v_mul_f32_e32 v42, v42, v74
	v_mul_f32_e32 v43, v43, v75
	v_mul_f32_e32 v44, v44, v76
	v_mul_f32_e32 v45, v45, v77
	v_mul_f32_e32 v46, v46, v78
	v_mul_f32_e32 v47, v47, v79
	v_mul_f32_e32 v48, v48, v64
	v_mul_f32_e32 v49, v49, v65
	v_mul_f32_e32 v50, v50, v66
	v_mul_f32_e32 v51, v51, v67
	v_mul_f32_e32 v52, v52, v68
	v_mul_f32_e32 v53, v53, v69
	v_mul_f32_e32 v54, v54, v70
	v_mul_f32_e32 v55, v55, v71
	v_mul_f32_e32 v56, v56, v72
	v_mul_f32_e32 v57, v57, v73
	v_mul_f32_e32 v58, v58, v74
	v_mul_f32_e32 v59, v59, v75
	v_mul_f32_e32 v60, v60, v76
	v_mul_f32_e32 v61, v61, v77
	v_mul_f32_e32 v62, v62, v78
	v_mul_f32_e32 v63, v63, v79
	s_barrier
	ds_write_b32 v85, v48
	ds_write_b32 v85, v49 offset:272
	ds_write_b32 v85, v50 offset:544
	ds_write_b32 v85, v51 offset:816
	ds_write_b32 v85, v52 offset:2176
	ds_write_b32 v85, v53 offset:2448
	ds_write_b32 v85, v54 offset:2720
	ds_write_b32 v85, v55 offset:2992
	ds_write_b32 v85, v56 offset:4352
	ds_write_b32 v85, v57 offset:4624
	ds_write_b32 v85, v58 offset:4896
	ds_write_b32 v85, v59 offset:5168
	ds_write_b32 v85, v60 offset:6528
	ds_write_b32 v85, v61 offset:6800
	ds_write_b32 v85, v62 offset:7072
	ds_write_b32 v85, v63 offset:7344
	ds_write_b32 v85, v32 offset:128
	ds_write_b32 v85, v33 offset:400
	ds_write_b32 v85, v34 offset:672
	ds_write_b32 v85, v35 offset:944
	ds_write_b32 v85, v36 offset:2304
	ds_write_b32 v85, v37 offset:2576
	ds_write_b32 v85, v38 offset:2848
	ds_write_b32 v85, v39 offset:3120
	ds_write_b32 v85, v40 offset:4480
	ds_write_b32 v85, v41 offset:4752
	ds_write_b32 v85, v42 offset:5024
	ds_write_b32 v85, v43 offset:5296
	ds_write_b32 v85, v44 offset:6656
	ds_write_b32 v85, v45 offset:6928
	ds_write_b32 v85, v46 offset:7200
	ds_write_b32 v85, v47 offset:7472
	s_waitcnt lgkmcnt(0)
	ds_read_b128 v[96:99], v86
	ds_read_b128 v[100:103], v86 offset:16
	ds_read_b128 v[104:107], v86 offset:32
	ds_read_b128 v[108:111], v86 offset:48
	ds_read_b128 v[112:115], v86 offset:64
	ds_read_b128 v[116:119], v86 offset:80
	ds_read_b128 v[120:123], v86 offset:96
	ds_read_b128 v[124:127], v86 offset:112
	s_waitcnt vmcnt(4) lgkmcnt(0)
	v_lshlrev_b32_e32 v186, 16, v128
	v_and_b32_e32 v187, 0xffff0000, v128
	v_lshlrev_b32_e32 v188, 16, v129
	v_and_b32_e32 v189, 0xffff0000, v129
	v_mul_f32_e32 v224, 0xbfb8aa3b, v186
	v_mul_f32_e32 v225, 0xbfb8aa3b, v187
	v_mul_f32_e32 v226, 0xbfb8aa3b, v188
	v_mul_f32_e32 v227, 0xbfb8aa3b, v189
	v_exp_f32_e32 v224, v224
	v_exp_f32_e32 v225, v225
	v_exp_f32_e32 v226, v226
	v_exp_f32_e32 v227, v227
	v_add_f32_e32 v224, 1.0, v224
	v_add_f32_e32 v225, 1.0, v225
	v_add_f32_e32 v226, 1.0, v226
	v_add_f32_e32 v227, 1.0, v227
	v_rcp_f32_e32 v224, v224
	v_rcp_f32_e32 v225, v225
	v_rcp_f32_e32 v226, v226
	v_rcp_f32_e32 v227, v227
	v_mul_f32_e32 v186, v224, v186
	v_mul_f32_e32 v187, v225, v187
	v_mul_f32_e32 v188, v226, v188
	v_mul_f32_e32 v189, v227, v189
	v_mul_f32_e32 v186, v96, v186
	v_mul_f32_e32 v187, v97, v187
	v_mul_f32_e32 v188, v98, v188
	v_mul_f32_e32 v189, v99, v189
	v_lshlrev_b32_e32 v190, 16, v130
	v_and_b32_e32 v191, 0xffff0000, v130
	v_lshlrev_b32_e32 v192, 16, v131
	v_and_b32_e32 v193, 0xffff0000, v131
	v_mul_f32_e32 v224, 0xbfb8aa3b, v190
	v_mul_f32_e32 v225, 0xbfb8aa3b, v191
	v_mul_f32_e32 v226, 0xbfb8aa3b, v192
	v_mul_f32_e32 v227, 0xbfb8aa3b, v193
	v_exp_f32_e32 v224, v224
	v_exp_f32_e32 v225, v225
	v_exp_f32_e32 v226, v226
	v_exp_f32_e32 v227, v227
	v_add_f32_e32 v224, 1.0, v224
	v_add_f32_e32 v225, 1.0, v225
	v_add_f32_e32 v226, 1.0, v226
	v_add_f32_e32 v227, 1.0, v227
	v_rcp_f32_e32 v224, v224
	v_rcp_f32_e32 v225, v225
	v_rcp_f32_e32 v226, v226
	v_rcp_f32_e32 v227, v227
	v_mul_f32_e32 v190, v224, v190
	v_mul_f32_e32 v191, v225, v191
	v_mul_f32_e32 v192, v226, v192
	v_mul_f32_e32 v193, v227, v193
	v_mul_f32_e32 v190, v100, v190
	v_mul_f32_e32 v191, v101, v191
	v_mul_f32_e32 v192, v102, v192
	v_mul_f32_e32 v193, v103, v193
	v_lshlrev_b32_e32 v194, 16, v132
	v_and_b32_e32 v195, 0xffff0000, v132
	v_lshlrev_b32_e32 v196, 16, v133
	v_and_b32_e32 v197, 0xffff0000, v133
	v_mul_f32_e32 v224, 0xbfb8aa3b, v194
	v_mul_f32_e32 v225, 0xbfb8aa3b, v195
	v_mul_f32_e32 v226, 0xbfb8aa3b, v196
	v_mul_f32_e32 v227, 0xbfb8aa3b, v197
	v_exp_f32_e32 v224, v224
	v_exp_f32_e32 v225, v225
	v_exp_f32_e32 v226, v226
	v_exp_f32_e32 v227, v227
	v_add_f32_e32 v224, 1.0, v224
	v_add_f32_e32 v225, 1.0, v225
	v_add_f32_e32 v226, 1.0, v226
	v_add_f32_e32 v227, 1.0, v227
	v_rcp_f32_e32 v224, v224
	v_rcp_f32_e32 v225, v225
	v_rcp_f32_e32 v226, v226
	v_rcp_f32_e32 v227, v227
	v_mul_f32_e32 v194, v224, v194
	v_mul_f32_e32 v195, v225, v195
	v_mul_f32_e32 v196, v226, v196
	v_mul_f32_e32 v197, v227, v197
	v_mul_f32_e32 v194, v104, v194
	v_mul_f32_e32 v195, v105, v195
	v_mul_f32_e32 v196, v106, v196
	v_mul_f32_e32 v197, v107, v197
	v_lshlrev_b32_e32 v198, 16, v134
	v_and_b32_e32 v199, 0xffff0000, v134
	v_lshlrev_b32_e32 v200, 16, v135
	v_and_b32_e32 v201, 0xffff0000, v135
	v_mul_f32_e32 v224, 0xbfb8aa3b, v198
	v_mul_f32_e32 v225, 0xbfb8aa3b, v199
	v_mul_f32_e32 v226, 0xbfb8aa3b, v200
	v_mul_f32_e32 v227, 0xbfb8aa3b, v201
	v_exp_f32_e32 v224, v224
	v_exp_f32_e32 v225, v225
	v_exp_f32_e32 v226, v226
	v_exp_f32_e32 v227, v227
	v_add_f32_e32 v224, 1.0, v224
	v_add_f32_e32 v225, 1.0, v225
	v_add_f32_e32 v226, 1.0, v226
	v_add_f32_e32 v227, 1.0, v227
	v_rcp_f32_e32 v224, v224
	v_rcp_f32_e32 v225, v225
	v_rcp_f32_e32 v226, v226
	v_rcp_f32_e32 v227, v227
	v_mul_f32_e32 v198, v224, v198
	v_mul_f32_e32 v199, v225, v199
	v_mul_f32_e32 v200, v226, v200
	v_mul_f32_e32 v201, v227, v201
	v_mul_f32_e32 v198, v108, v198
	v_mul_f32_e32 v199, v109, v199
	v_mul_f32_e32 v200, v110, v200
	v_mul_f32_e32 v201, v111, v201
	v_lshlrev_b32_e32 v202, 16, v136
	v_and_b32_e32 v203, 0xffff0000, v136
	v_lshlrev_b32_e32 v204, 16, v137
	v_and_b32_e32 v205, 0xffff0000, v137
	v_mul_f32_e32 v224, 0xbfb8aa3b, v202
	v_mul_f32_e32 v225, 0xbfb8aa3b, v203
	v_mul_f32_e32 v226, 0xbfb8aa3b, v204
	v_mul_f32_e32 v227, 0xbfb8aa3b, v205
	v_exp_f32_e32 v224, v224
	v_exp_f32_e32 v225, v225
	v_exp_f32_e32 v226, v226
	v_exp_f32_e32 v227, v227
	v_add_f32_e32 v224, 1.0, v224
	v_add_f32_e32 v225, 1.0, v225
	v_add_f32_e32 v226, 1.0, v226
	v_add_f32_e32 v227, 1.0, v227
	v_rcp_f32_e32 v224, v224
	v_rcp_f32_e32 v225, v225
	v_rcp_f32_e32 v226, v226
	v_rcp_f32_e32 v227, v227
	v_mul_f32_e32 v202, v224, v202
	v_mul_f32_e32 v203, v225, v203
	v_mul_f32_e32 v204, v226, v204
	v_mul_f32_e32 v205, v227, v205
	v_mul_f32_e32 v202, v112, v202
	v_mul_f32_e32 v203, v113, v203
	v_mul_f32_e32 v204, v114, v204
	v_mul_f32_e32 v205, v115, v205
	v_lshlrev_b32_e32 v206, 16, v138
	v_and_b32_e32 v207, 0xffff0000, v138
	v_lshlrev_b32_e32 v208, 16, v139
	v_and_b32_e32 v209, 0xffff0000, v139
	v_mul_f32_e32 v224, 0xbfb8aa3b, v206
	v_mul_f32_e32 v225, 0xbfb8aa3b, v207
	v_mul_f32_e32 v226, 0xbfb8aa3b, v208
	v_mul_f32_e32 v227, 0xbfb8aa3b, v209
	v_exp_f32_e32 v224, v224
	v_exp_f32_e32 v225, v225
	v_exp_f32_e32 v226, v226
	v_exp_f32_e32 v227, v227
	v_add_f32_e32 v224, 1.0, v224
	v_add_f32_e32 v225, 1.0, v225
	v_add_f32_e32 v226, 1.0, v226
	v_add_f32_e32 v227, 1.0, v227
	v_rcp_f32_e32 v224, v224
	v_rcp_f32_e32 v225, v225
	v_rcp_f32_e32 v226, v226
	v_rcp_f32_e32 v227, v227
	v_mul_f32_e32 v206, v224, v206
	v_mul_f32_e32 v207, v225, v207
	v_mul_f32_e32 v208, v226, v208
	v_mul_f32_e32 v209, v227, v209
	v_mul_f32_e32 v206, v116, v206
	v_mul_f32_e32 v207, v117, v207
	v_mul_f32_e32 v208, v118, v208
	v_mul_f32_e32 v209, v119, v209
	v_lshlrev_b32_e32 v210, 16, v140
	v_and_b32_e32 v211, 0xffff0000, v140
	v_lshlrev_b32_e32 v212, 16, v141
	v_and_b32_e32 v213, 0xffff0000, v141
	v_mul_f32_e32 v224, 0xbfb8aa3b, v210
	v_mul_f32_e32 v225, 0xbfb8aa3b, v211
	v_mul_f32_e32 v226, 0xbfb8aa3b, v212
	v_mul_f32_e32 v227, 0xbfb8aa3b, v213
	v_exp_f32_e32 v224, v224
	v_exp_f32_e32 v225, v225
	v_exp_f32_e32 v226, v226
	v_exp_f32_e32 v227, v227
	v_add_f32_e32 v224, 1.0, v224
	v_add_f32_e32 v225, 1.0, v225
	v_add_f32_e32 v226, 1.0, v226
	v_add_f32_e32 v227, 1.0, v227
	v_rcp_f32_e32 v224, v224
	v_rcp_f32_e32 v225, v225
	v_rcp_f32_e32 v226, v226
	v_rcp_f32_e32 v227, v227
	v_mul_f32_e32 v210, v224, v210
	v_mul_f32_e32 v211, v225, v211
	v_mul_f32_e32 v212, v226, v212
	v_mul_f32_e32 v213, v227, v213
	v_mul_f32_e32 v210, v120, v210
	v_mul_f32_e32 v211, v121, v211
	v_mul_f32_e32 v212, v122, v212
	v_mul_f32_e32 v213, v123, v213
	v_lshlrev_b32_e32 v214, 16, v142
	v_and_b32_e32 v215, 0xffff0000, v142
	v_lshlrev_b32_e32 v216, 16, v143
	v_and_b32_e32 v217, 0xffff0000, v143
	v_mul_f32_e32 v224, 0xbfb8aa3b, v214
	v_mul_f32_e32 v225, 0xbfb8aa3b, v215
	v_mul_f32_e32 v226, 0xbfb8aa3b, v216
	v_mul_f32_e32 v227, 0xbfb8aa3b, v217
	v_exp_f32_e32 v224, v224
	v_exp_f32_e32 v225, v225
	v_exp_f32_e32 v226, v226
	v_exp_f32_e32 v227, v227
	v_add_f32_e32 v224, 1.0, v224
	v_add_f32_e32 v225, 1.0, v225
	v_add_f32_e32 v226, 1.0, v226
	v_add_f32_e32 v227, 1.0, v227
	v_rcp_f32_e32 v224, v224
	v_rcp_f32_e32 v225, v225
	v_rcp_f32_e32 v226, v226
	v_rcp_f32_e32 v227, v227
	v_mul_f32_e32 v214, v224, v214
	v_mul_f32_e32 v215, v225, v215
	v_mul_f32_e32 v216, v226, v216
	v_mul_f32_e32 v217, v227, v217
	v_mul_f32_e32 v214, v124, v214
	v_mul_f32_e32 v215, v125, v215
	v_mul_f32_e32 v216, v126, v216
	v_mul_f32_e32 v217, v127, v217
	v_cvt_pk_bf16_f32 v96, v186, v187
	v_cvt_pk_bf16_f32 v97, v188, v189
	v_cvt_pk_bf16_f32 v98, v190, v191
	v_cvt_pk_bf16_f32 v99, v192, v193
	v_cvt_pk_bf16_f32 v100, v194, v195
	v_cvt_pk_bf16_f32 v101, v196, v197
	v_cvt_pk_bf16_f32 v102, v198, v199
	v_cvt_pk_bf16_f32 v103, v200, v201
	v_cvt_pk_bf16_f32 v104, v202, v203
	v_cvt_pk_bf16_f32 v105, v204, v205
	v_cvt_pk_bf16_f32 v106, v206, v207
	v_cvt_pk_bf16_f32 v107, v208, v209
	v_cvt_pk_bf16_f32 v108, v210, v211
	v_cvt_pk_bf16_f32 v109, v212, v213
	v_cvt_pk_bf16_f32 v110, v214, v215
	v_cvt_pk_bf16_f32 v111, v216, v217
	global_store_dwordx4 v[90:91], v[96:99], off offset:0
	global_store_dwordx4 v[90:91], v[100:103], off offset:16
	global_store_dwordx4 v[90:91], v[104:107], off offset:32
	global_store_dwordx4 v[90:91], v[108:111], off offset:48
	ds_write_b32 v85, v16
	ds_write_b32 v85, v17 offset:272
	ds_write_b32 v85, v18 offset:544
	ds_write_b32 v85, v19 offset:816
	ds_write_b32 v85, v20 offset:2176
	ds_write_b32 v85, v21 offset:2448
	ds_write_b32 v85, v22 offset:2720
	ds_write_b32 v85, v23 offset:2992
	ds_write_b32 v85, v24 offset:4352
	ds_write_b32 v85, v25 offset:4624
	ds_write_b32 v85, v26 offset:4896
	ds_write_b32 v85, v27 offset:5168
	ds_write_b32 v85, v28 offset:6528
	ds_write_b32 v85, v29 offset:6800
	ds_write_b32 v85, v30 offset:7072
	ds_write_b32 v85, v31 offset:7344
	ds_write_b32 v85, v0 offset:128
	ds_write_b32 v85, v1 offset:400
	ds_write_b32 v85, v2 offset:672
	ds_write_b32 v85, v3 offset:944
	ds_write_b32 v85, v4 offset:2304
	ds_write_b32 v85, v5 offset:2576
	ds_write_b32 v85, v6 offset:2848
	ds_write_b32 v85, v7 offset:3120
	ds_write_b32 v85, v8 offset:4480
	ds_write_b32 v85, v9 offset:4752
	ds_write_b32 v85, v10 offset:5024
	ds_write_b32 v85, v11 offset:5296
	ds_write_b32 v85, v12 offset:6656
	ds_write_b32 v85, v13 offset:6928
	ds_write_b32 v85, v14 offset:7200
	ds_write_b32 v85, v15 offset:7472
	s_waitcnt lgkmcnt(0)
	ds_read_b128 v[96:99], v86
	ds_read_b128 v[100:103], v86 offset:16
	ds_read_b128 v[104:107], v86 offset:32
	ds_read_b128 v[108:111], v86 offset:48
	ds_read_b128 v[112:115], v86 offset:64
	ds_read_b128 v[116:119], v86 offset:80
	ds_read_b128 v[120:123], v86 offset:96
	ds_read_b128 v[124:127], v86 offset:112
	s_waitcnt vmcnt(4) lgkmcnt(0)
	v_lshlrev_b32_e32 v186, 16, v144
	v_and_b32_e32 v187, 0xffff0000, v144
	v_lshlrev_b32_e32 v188, 16, v145
	v_and_b32_e32 v189, 0xffff0000, v145
	v_mul_f32_e32 v224, 0xbfb8aa3b, v186
	v_mul_f32_e32 v225, 0xbfb8aa3b, v187
	v_mul_f32_e32 v226, 0xbfb8aa3b, v188
	v_mul_f32_e32 v227, 0xbfb8aa3b, v189
	v_exp_f32_e32 v224, v224
	v_exp_f32_e32 v225, v225
	v_exp_f32_e32 v226, v226
	v_exp_f32_e32 v227, v227
	v_add_f32_e32 v224, 1.0, v224
	v_add_f32_e32 v225, 1.0, v225
	v_add_f32_e32 v226, 1.0, v226
	v_add_f32_e32 v227, 1.0, v227
	v_rcp_f32_e32 v224, v224
	v_rcp_f32_e32 v225, v225
	v_rcp_f32_e32 v226, v226
	v_rcp_f32_e32 v227, v227
	v_mul_f32_e32 v186, v224, v186
	v_mul_f32_e32 v187, v225, v187
	v_mul_f32_e32 v188, v226, v188
	v_mul_f32_e32 v189, v227, v189
	v_mul_f32_e32 v186, v96, v186
	v_mul_f32_e32 v187, v97, v187
	v_mul_f32_e32 v188, v98, v188
	v_mul_f32_e32 v189, v99, v189
	v_lshlrev_b32_e32 v190, 16, v146
	v_and_b32_e32 v191, 0xffff0000, v146
	v_lshlrev_b32_e32 v192, 16, v147
	v_and_b32_e32 v193, 0xffff0000, v147
	v_mul_f32_e32 v224, 0xbfb8aa3b, v190
	v_mul_f32_e32 v225, 0xbfb8aa3b, v191
	v_mul_f32_e32 v226, 0xbfb8aa3b, v192
	v_mul_f32_e32 v227, 0xbfb8aa3b, v193
	v_exp_f32_e32 v224, v224
	v_exp_f32_e32 v225, v225
	v_exp_f32_e32 v226, v226
	v_exp_f32_e32 v227, v227
	v_add_f32_e32 v224, 1.0, v224
	v_add_f32_e32 v225, 1.0, v225
	v_add_f32_e32 v226, 1.0, v226
	v_add_f32_e32 v227, 1.0, v227
	v_rcp_f32_e32 v224, v224
	v_rcp_f32_e32 v225, v225
	v_rcp_f32_e32 v226, v226
	v_rcp_f32_e32 v227, v227
	v_mul_f32_e32 v190, v224, v190
	v_mul_f32_e32 v191, v225, v191
	v_mul_f32_e32 v192, v226, v192
	v_mul_f32_e32 v193, v227, v193
	v_mul_f32_e32 v190, v100, v190
	v_mul_f32_e32 v191, v101, v191
	v_mul_f32_e32 v192, v102, v192
	v_mul_f32_e32 v193, v103, v193
	v_lshlrev_b32_e32 v194, 16, v148
	v_and_b32_e32 v195, 0xffff0000, v148
	v_lshlrev_b32_e32 v196, 16, v149
	v_and_b32_e32 v197, 0xffff0000, v149
	v_mul_f32_e32 v224, 0xbfb8aa3b, v194
	v_mul_f32_e32 v225, 0xbfb8aa3b, v195
	v_mul_f32_e32 v226, 0xbfb8aa3b, v196
	v_mul_f32_e32 v227, 0xbfb8aa3b, v197
	v_exp_f32_e32 v224, v224
	v_exp_f32_e32 v225, v225
	v_exp_f32_e32 v226, v226
	v_exp_f32_e32 v227, v227
	v_add_f32_e32 v224, 1.0, v224
	v_add_f32_e32 v225, 1.0, v225
	v_add_f32_e32 v226, 1.0, v226
	v_add_f32_e32 v227, 1.0, v227
	v_rcp_f32_e32 v224, v224
	v_rcp_f32_e32 v225, v225
	v_rcp_f32_e32 v226, v226
	v_rcp_f32_e32 v227, v227
	v_mul_f32_e32 v194, v224, v194
	v_mul_f32_e32 v195, v225, v195
	v_mul_f32_e32 v196, v226, v196
	v_mul_f32_e32 v197, v227, v197
	v_mul_f32_e32 v194, v104, v194
	v_mul_f32_e32 v195, v105, v195
	v_mul_f32_e32 v196, v106, v196
	v_mul_f32_e32 v197, v107, v197
	v_lshlrev_b32_e32 v198, 16, v150
	v_and_b32_e32 v199, 0xffff0000, v150
	v_lshlrev_b32_e32 v200, 16, v151
	v_and_b32_e32 v201, 0xffff0000, v151
	v_mul_f32_e32 v224, 0xbfb8aa3b, v198
	v_mul_f32_e32 v225, 0xbfb8aa3b, v199
	v_mul_f32_e32 v226, 0xbfb8aa3b, v200
	v_mul_f32_e32 v227, 0xbfb8aa3b, v201
	v_exp_f32_e32 v224, v224
	v_exp_f32_e32 v225, v225
	v_exp_f32_e32 v226, v226
	v_exp_f32_e32 v227, v227
	v_add_f32_e32 v224, 1.0, v224
	v_add_f32_e32 v225, 1.0, v225
	v_add_f32_e32 v226, 1.0, v226
	v_add_f32_e32 v227, 1.0, v227
	v_rcp_f32_e32 v224, v224
	v_rcp_f32_e32 v225, v225
	v_rcp_f32_e32 v226, v226
	v_rcp_f32_e32 v227, v227
	v_mul_f32_e32 v198, v224, v198
	v_mul_f32_e32 v199, v225, v199
	v_mul_f32_e32 v200, v226, v200
	v_mul_f32_e32 v201, v227, v201
	v_mul_f32_e32 v198, v108, v198
	v_mul_f32_e32 v199, v109, v199
	v_mul_f32_e32 v200, v110, v200
	v_mul_f32_e32 v201, v111, v201
	v_lshlrev_b32_e32 v202, 16, v152
	v_and_b32_e32 v203, 0xffff0000, v152
	v_lshlrev_b32_e32 v204, 16, v153
	v_and_b32_e32 v205, 0xffff0000, v153
	v_mul_f32_e32 v224, 0xbfb8aa3b, v202
	v_mul_f32_e32 v225, 0xbfb8aa3b, v203
	v_mul_f32_e32 v226, 0xbfb8aa3b, v204
	v_mul_f32_e32 v227, 0xbfb8aa3b, v205
	v_exp_f32_e32 v224, v224
	v_exp_f32_e32 v225, v225
	v_exp_f32_e32 v226, v226
	v_exp_f32_e32 v227, v227
	v_add_f32_e32 v224, 1.0, v224
	v_add_f32_e32 v225, 1.0, v225
	v_add_f32_e32 v226, 1.0, v226
	v_add_f32_e32 v227, 1.0, v227
	v_rcp_f32_e32 v224, v224
	v_rcp_f32_e32 v225, v225
	v_rcp_f32_e32 v226, v226
	v_rcp_f32_e32 v227, v227
	v_mul_f32_e32 v202, v224, v202
	v_mul_f32_e32 v203, v225, v203
	v_mul_f32_e32 v204, v226, v204
	v_mul_f32_e32 v205, v227, v205
	v_mul_f32_e32 v202, v112, v202
	v_mul_f32_e32 v203, v113, v203
	v_mul_f32_e32 v204, v114, v204
	v_mul_f32_e32 v205, v115, v205
	v_lshlrev_b32_e32 v206, 16, v154
	v_and_b32_e32 v207, 0xffff0000, v154
	v_lshlrev_b32_e32 v208, 16, v155
	v_and_b32_e32 v209, 0xffff0000, v155
	v_mul_f32_e32 v224, 0xbfb8aa3b, v206
	v_mul_f32_e32 v225, 0xbfb8aa3b, v207
	v_mul_f32_e32 v226, 0xbfb8aa3b, v208
	v_mul_f32_e32 v227, 0xbfb8aa3b, v209
	v_exp_f32_e32 v224, v224
	v_exp_f32_e32 v225, v225
	v_exp_f32_e32 v226, v226
	v_exp_f32_e32 v227, v227
	v_add_f32_e32 v224, 1.0, v224
	v_add_f32_e32 v225, 1.0, v225
	v_add_f32_e32 v226, 1.0, v226
	v_add_f32_e32 v227, 1.0, v227
	v_rcp_f32_e32 v224, v224
	v_rcp_f32_e32 v225, v225
	v_rcp_f32_e32 v226, v226
	v_rcp_f32_e32 v227, v227
	v_mul_f32_e32 v206, v224, v206
	v_mul_f32_e32 v207, v225, v207
	v_mul_f32_e32 v208, v226, v208
	v_mul_f32_e32 v209, v227, v209
	v_mul_f32_e32 v206, v116, v206
	v_mul_f32_e32 v207, v117, v207
	v_mul_f32_e32 v208, v118, v208
	v_mul_f32_e32 v209, v119, v209
	v_lshlrev_b32_e32 v210, 16, v156
	v_and_b32_e32 v211, 0xffff0000, v156
	v_lshlrev_b32_e32 v212, 16, v157
	v_and_b32_e32 v213, 0xffff0000, v157
	v_mul_f32_e32 v224, 0xbfb8aa3b, v210
	v_mul_f32_e32 v225, 0xbfb8aa3b, v211
	v_mul_f32_e32 v226, 0xbfb8aa3b, v212
	v_mul_f32_e32 v227, 0xbfb8aa3b, v213
	v_exp_f32_e32 v224, v224
	v_exp_f32_e32 v225, v225
	v_exp_f32_e32 v226, v226
	v_exp_f32_e32 v227, v227
	v_add_f32_e32 v224, 1.0, v224
	v_add_f32_e32 v225, 1.0, v225
	v_add_f32_e32 v226, 1.0, v226
	v_add_f32_e32 v227, 1.0, v227
	v_rcp_f32_e32 v224, v224
	v_rcp_f32_e32 v225, v225
	v_rcp_f32_e32 v226, v226
	v_rcp_f32_e32 v227, v227
	v_mul_f32_e32 v210, v224, v210
	v_mul_f32_e32 v211, v225, v211
	v_mul_f32_e32 v212, v226, v212
	v_mul_f32_e32 v213, v227, v213
	v_mul_f32_e32 v210, v120, v210
	v_mul_f32_e32 v211, v121, v211
	v_mul_f32_e32 v212, v122, v212
	v_mul_f32_e32 v213, v123, v213
	v_lshlrev_b32_e32 v214, 16, v158
	v_and_b32_e32 v215, 0xffff0000, v158
	v_lshlrev_b32_e32 v216, 16, v159
	v_and_b32_e32 v217, 0xffff0000, v159
	v_mul_f32_e32 v224, 0xbfb8aa3b, v214
	v_mul_f32_e32 v225, 0xbfb8aa3b, v215
	v_mul_f32_e32 v226, 0xbfb8aa3b, v216
	v_mul_f32_e32 v227, 0xbfb8aa3b, v217
	v_exp_f32_e32 v224, v224
	v_exp_f32_e32 v225, v225
	v_exp_f32_e32 v226, v226
	v_exp_f32_e32 v227, v227
	v_add_f32_e32 v224, 1.0, v224
	v_add_f32_e32 v225, 1.0, v225
	v_add_f32_e32 v226, 1.0, v226
	v_add_f32_e32 v227, 1.0, v227
	v_rcp_f32_e32 v224, v224
	v_rcp_f32_e32 v225, v225
	v_rcp_f32_e32 v226, v226
	v_rcp_f32_e32 v227, v227
	v_mul_f32_e32 v214, v224, v214
	v_mul_f32_e32 v215, v225, v215
	v_mul_f32_e32 v216, v226, v216
	v_mul_f32_e32 v217, v227, v217
	v_mul_f32_e32 v214, v124, v214
	v_mul_f32_e32 v215, v125, v215
	v_mul_f32_e32 v216, v126, v216
	v_mul_f32_e32 v217, v127, v217
	v_cvt_pk_bf16_f32 v96, v186, v187
	v_cvt_pk_bf16_f32 v97, v188, v189
	v_cvt_pk_bf16_f32 v98, v190, v191
	v_cvt_pk_bf16_f32 v99, v192, v193
	v_cvt_pk_bf16_f32 v100, v194, v195
	v_cvt_pk_bf16_f32 v101, v196, v197
	v_cvt_pk_bf16_f32 v102, v198, v199
	v_cvt_pk_bf16_f32 v103, v200, v201
	v_cvt_pk_bf16_f32 v104, v202, v203
	v_cvt_pk_bf16_f32 v105, v204, v205
	v_cvt_pk_bf16_f32 v106, v206, v207
	v_cvt_pk_bf16_f32 v107, v208, v209
	v_cvt_pk_bf16_f32 v108, v210, v211
	v_cvt_pk_bf16_f32 v109, v212, v213
	v_cvt_pk_bf16_f32 v110, v214, v215
	v_cvt_pk_bf16_f32 v111, v216, v217
	global_store_dwordx4 v[90:91], v[96:99], off offset:128
	global_store_dwordx4 v[90:91], v[100:103], off offset:144
	global_store_dwordx4 v[90:91], v[104:107], off offset:160
	global_store_dwordx4 v[90:91], v[108:111], off offset:176
	s_add_i32 s4, s62, 1
	s_cmp_lt_u32 s62, 2
	s_mov_b32 s62, s4
	s_cselect_b64 s[2:3], -1, 0
	s_and_b64 s[2:3], s[0:1], s[2:3]
	s_andn2_b64 vcc, exec, s[2:3]
	s_setprio 0
	s_waitcnt vmcnt(63) expcnt(7) lgkmcnt(15)
	s_barrier
	s_cbranch_vccnz .LBB0_1353
